# seams 2,9 (W_in->mixer) use a halo flavor: even group's last arriver writes back its L2 and bumps a second counter, odd groups wait for own group + that counter; every in-loop seam is now group-based
# speedup vs baseline: 1.0159x; 1.0077x over previous
.LBB0_515:
	s_mov_b32 s99, 0
	s_waitcnt vmcnt(0)
	s_waitcnt vmcnt(0) lgkmcnt(0)
	s_barrier
	s_and_saveexec_b64 s[0:1], s[62:63]
	s_cbranch_execz .LBB0_202
	v_readlane_b32 s6, v254, 49
	s_cmp_eq_u32 s100, 1
	s_cbranch_scc0 .Lgbar
	s_add_i32 s9, s6, 1
	s_lshl_b32 s9, s9, 5
	v_readlane_b32 s8, v252, 0
	v_readlane_b32 s10, v252, 45
	v_readlane_b32 s11, v252, 46
	s_and_b32 s8, s8, 7
	s_add_u32 s10, s10, 0xe3600
	s_addc_u32 s11, s11, 0
	s_lshl_b32 s13, 1, s8
	s_lshl_b32 s14, s8, 6
	v_mov_b32_e32 v1, 1
	v_mov_b32_e32 v2, s14
	s_cmp_eq_u32 s6, 2
	s_cbranch_scc1 .Llb_h
	s_cmp_eq_u32 s6, 9
	s_cbranch_scc1 .Llb_h
	s_mov_b32 s16, 0x0e060301
	s_mov_b32 s17, 0xb058281c
	s_cmp_eq_u32 s6, 1
	s_cbranch_scc1 .Llb_tab
	s_mov_b32 s16, 0x0a060301
	s_mov_b32 s17, 0x88482414
	s_cmp_eq_u32 s6, 6
	s_cbranch_scc1 .Llb_tab
	s_mov_b32 s16, 0x0c060301
	s_mov_b32 s17, 0xa070381c
	s_cmp_eq_u32 s6, 8
	s_cbranch_scc1 .Llb_tab
	s_mov_b32 s16, 0xf83c1e07
	s_mov_b32 s17, 0x8040a0d0
	s_cmp_eq_u32 s6, 4
	s_cbranch_scc1 .Llb_tab
	s_mov_b32 s16, 0x783c0e07
	s_mov_b32 s17, 0x8040e0f0
	s_cmp_eq_u32 s6, 11
	s_cbranch_scc1 .Llb_tab
	s_branch .Llb_have
.Llb_tab:
	s_lshl_b32 s15, s8, 3
	s_lshr_b64 s[16:17], s[16:17], s15
	s_and_b32 s16, s16, 0xff
	s_andn2_b32 s16, s16, s13
	s_cmp_eq_u32 s16, 0
	s_cbranch_scc1 .Llb_have
	s_lshl_b32 s16, s16, 16
	s_or_b32 s99, s16, s9
.Llb_have:
	global_atomic_add v2, v1, s[10:11]
	s_mov_b32 s17, 0x300
	s_mov_b32 s15, 0
	s_branch .Llb_pollsetup
.Llb_h:
	s_mov_b32 s15, 1
	s_cmp_eq_u32 s6, 9
	s_cselect_b32 s15, 2, s15
	global_atomic_add v0, v2, v1, s[10:11] sc0
	s_waitcnt vmcnt(0)
	v_readfirstlane_b32 s16, v0
	s_and_b32 s17, s8, 1
	s_add_i32 s16, s16, 1
	s_cmp_eq_u32 s16, s9
	s_cbranch_scc0 .Llb_h_notlast
	s_cmp_eq_u32 s17, 0
	s_cbranch_scc0 .Llb_h_notlast
	buffer_wbl2 sc1
	s_waitcnt vmcnt(0)
	s_add_i32 s16, s14, 0x300
	v_mov_b32_e32 v2, s16
	s_nop 0
	global_atomic_add v2, v1, s[10:11]
.Llb_h_notlast:
	s_lshl_b32 s16, s17, 8
	s_or_b32 s13, s13, s16
	s_add_i32 s17, s14, 0x2c0
.Llb_pollsetup:
	s_mov_b64 exec, 0x1ff
	v_mbcnt_lo_u32_b32 v2, -1, 0
	v_lshlrev_b32_e32 v2, 6, v2
	v_mov_b32_e32 v3, s9
	s_nop 0
	v_writelane_b32 v2, s17, 8
	v_writelane_b32 v3, s15, 8
	s_mov_b32 s12, 0
.Llb_poll:
	global_load_dword v0, v2, s[10:11] sc1
	s_waitcnt vmcnt(0)
	v_cmp_le_u32_e32 vcc, v3, v0
	s_nop 1
	s_and_b32 s8, vcc_lo, s13
	s_cmp_eq_u32 s8, s13
	s_cbranch_scc1 .Llb_done
	s_sleep 1
	s_add_i32 s12, s12, 1
	s_cmp_lt_u32 s12, 0x8000
	s_cbranch_scc1 .Llb_poll
